# weight conversion schedule: ffn-up-gap workgroups convert the current layer's ffn-down weights (last layer's gap used, 704 fewer jobs in phase 0)
# speedup vs baseline: 1.0069x; 1.0069x over previous
; #define LAS __attribute__((address_space(3)))
; __device__ __forceinline__ int opaque_tid() { int t = threadIdx.x; asm volatile("" : "+v"(t)); return t; }
; template <bool PREPMAP> __device__ __forceinline__ int cvt_map(int q) {
;     if (!PREPMAP) return q;
;     constexpr int NL = (NLAYER - 1) * GAP_PRE;
;     if (q >= NL) return q - NL;
;     return (1 + q / GAP_PRE) * CT_LAYER + q % GAP_PRE;
; }
; template <bool PREPMAP>
; __device__ __forceinline__ void convert_jobs(const Params& p, int job0, int job_end, int stride, LAS unsigned char* lds) {
;     if (job0 >= job_end) return;
;     const int tid = opaque_tid();
;     int job = job0;
;     CvtJob cur = cvt_decode(p, cvt_map<PREPMAP>(job));
.LBB0_11:
	s_or_b64 exec, exec, s[4:5]
	s_mov_b32 s24, s80
	s_cmpk_gt_i32 s80, 0x1592
	s_cbranch_scc1 .LBB0_197
	v_mov_b32_e32 v36, v210
	s_cmpk_lt_i32 s80, 0xf3c
	s_cbranch_scc0 .LBB0_14
	s_mul_hi_i32 s4, s80, 0x64d319ff
	s_lshr_b32 s5, s4, 31
	s_ashr_i32 s4, s4, 9
	s_add_i32 s4, s4, s5
	s_mul_i32 s5, s4, 0xc50
	s_mulk_i32 s4, 0x514
	s_sub_i32 s4, s80, s4
	s_add_i32 s4, s4, s5
	s_add_i32 s7, s4, 0xc50
	s_cbranch_execz .LBB0_15
	s_branch .LBB0_16

; template <bool PREPMAP> __device__ __forceinline__ int cvt_map(int q) {
;     if (!PREPMAP) return q;
;     constexpr int NL = (NLAYER - 1) * GAP_PRE;
;     if (q >= NL) return q - NL;
;     return (1 + q / GAP_PRE) * CT_LAYER + q % GAP_PRE;
; }
; template <bool PREPMAP>
; __device__ __forceinline__ void convert_jobs(const Params& p, int job0, int job_end, int stride, LAS unsigned char* lds) {
;     ...
;     for (;;) {
;         const int nj = job + stride; const bool more = nj < job_end;
;         CvtJob nxt = cur; f32x4 v2[8]; float gk2[8];
;         if (more) { nxt = cvt_decode(p, cvt_map<PREPMAP>(nj)); cvt_load(nxt, tid, v2, gk2); }
.LBB0_106:
	s_load_dwordx2 s[4:5], s[0:1], 0xb0
	s_mov_b64 s[48:49], s[34:35]
	s_mov_b32 s66, s25
	s_mov_b32 s56, s36
	s_mov_b32 s67, s33
	s_waitcnt lgkmcnt(0)
	s_add_i32 s65, s24, s4
	s_cmpk_lt_i32 s65, 0x1593
	s_cselect_b64 s[46:47], -1, 0
	s_cmpk_gt_i32 s65, 0x1592
	s_cselect_b64 s[44:45], -1, 0
	s_and_b64 vcc, exec, s[44:45]
	s_cbranch_vccnz .LBB0_194
	s_cmpk_lt_i32 s65, 0xf3c
	s_mov_b64 s[4:5], -1
	s_cbranch_scc0 .LBB0_109
	s_mul_hi_i32 s4, s65, 0x64d319ff
	s_lshr_b32 s5, s4, 31
	s_ashr_i32 s4, s4, 9
	s_add_i32 s4, s4, s5
	s_mul_i32 s5, s4, 0xc50
	s_mulk_i32 s4, 0x514
	s_sub_i32 s4, s65, s4
	s_add_i32 s4, s4, s5
	s_add_i32 s7, s4, 0xc50
	s_mov_b64 s[4:5], 0

; #define LAS __attribute__((address_space(3)))
; __device__ __forceinline__ CvtJob cvt_decode(const Params& p, int job) {
;     CvtJob j; j.gain = nullptr;
;     const int layer = job / CT_LAYER; int r = job % CT_LAYER;
;     unsigned char* wl = p.ws + WS_W + (size_t)layer * WL_SIZE;
;     if (r < CT_IN) { j.mat = 0; j.K = 2048; j.Nsrc = INC; j.W = p.in[I_WIN] + (size_t)layer * 2048 * INC; j.gain = p.in[I_LNMIXPRE] + layer * 2048; j.dst = (bf16_t*)(wl + WL_IN); }
;     else if ((r -= CT_IN) < CT_QUP) { j.mat = 1; j.K = 512; j.Nsrc = 1536; j.W = p.in[I_WQUP] + (size_t)layer * 512 * 1536; j.gain = p.in[I_GQL] + layer * 512; j.dst = (bf16_t*)(wl + WL_QUP); }
;     else if ((r -= CT_QUP) < CT_KVUP) { j.mat = 2; j.K = 512; j.Nsrc = 2048; j.W = p.in[I_WKVUP] + (size_t)layer * 512 * 2048; j.gain = p.in[I_GKVL] + layer * 512; j.dst = (bf16_t*)(wl + WL_KVUP); }
;     else if ((r -= CT_KVUP) < CT_OUT) { j.mat = 3; j.K = 2048; j.Nsrc = 2048; j.W = p.in[I_WOUT] + (size_t)layer * 2048 * 2048; j.dst = (bf16_t*)(wl + WL_OUT); }
;     else if ((r -= CT_OUT) < CT_UP) { j.mat = 4; j.K = 2048; j.Nsrc = DFF2; j.W = p.in[I_WUP] + (size_t)layer * 2048 * DFF2; j.gain = p.in[I_LNFFNPRE] + layer * 2048; j.dst = (bf16_t*)(wl + WL_UP); }
;     else { r -= CT_UP; j.mat = 5; j.K = DFF; j.Nsrc = 2048; j.W = p.in[I_WDOWN] + (size_t)layer * DFF * 2048; j.dst = (bf16_t*)(wl + WL_DOWN); }
;     const int nKt = j.K / 128, kt = r % nKt, ntile = r / nKt; j.k0 = kt * 128; j.n0 = ntile * 128;
; __device__ __forceinline__ void convert_gap(const Params& p, int layer, int nwg, int base, int per, LAS unsigned char* lds) {
;     if (layer + 1 >= NLAYER) return;
;     const int G = gridDim.x, c = blockIdx.x, rem = nwg % G;
;     const int limit = base == GAP_PRE ? GAP_BASE6 : CT_LAYER;
;     if (rem == 0) { __syncthreads(); convert_jobs<false>(p, (layer + 1) * CT_LAYER + base + c, (layer + 1) * CT_LAYER + limit, G, lds); return; }
;     if (c < rem) return;
;     const int slot = c - rem, nslots = G - rem;
;     int j0 = base + slot * per, j1 = j0 + per;
;     if (slot == nslots - 1 || j1 > limit) j1 = limit;
;     if (j0 > limit) j0 = limit;
;     __syncthreads();
;     convert_jobs<false>(p, (layer + 1) * CT_LAYER + j0, (layer + 1) * CT_LAYER + j1, 1, lds);
.LBB0_407:
	s_cmpk_gt_i32 s31, 0x7f
	s_cbranch_scc1 .LBB0_762
	v_readlane_b32 s0, v253, 46
	v_readlane_b32 s1, v253, 47
	s_add_i32 s2, s90, 1
	s_and_b64 vcc, exec, s[0:1]
	s_cbranch_vccz .LBB0_419
	v_readlane_b32 s0, v253, 48
	v_readlane_b32 s1, v253, 49
	s_andn2_b64 vcc, exec, s[0:1]
	s_cbranch_vccnz .LBB0_586
	v_readlane_b32 s0, v253, 52
	v_readlane_b32 s1, v253, 53
	s_andn2_b64 vcc, exec, s[0:1]
	s_waitcnt vmcnt(0) lgkmcnt(0)
	s_barrier
	s_cbranch_vccnz .LBB0_586
	s_mul_i32 s3, s2, 0xc50
	v_readlane_b32 s0, v253, 51
	s_cmp_eq_u32 s90, 3
	s_cselect_b32 s100, 0x990, 0
	s_max_i32 s0, s0, s100
	v_readlane_b32 s101, v253, 50
	s_nop 0
	s_cmp_ge_i32 s0, s101
	s_cbranch_scc1 .LBB0_762
	s_add_i32 s14, s0, s3
	s_mul_hi_i32 s0, s14, 0x532ae21d
	s_lshr_b32 s1, s0, 31
	s_ashr_i32 s0, s0, 10
	s_add_i32 s8, s0, s1
	v_mul_i32_i24_e32 v0, s8, v218
	s_ashr_i32 s9, s8, 31
	v_readfirstlane_b32 s0, v0
	s_sub_i32 s12, s14, s0
	s_cmpk_gt_i32 s12, 0x98f
	s_cselect_b32 s100, 1, 0
	s_sub_i32 s8, s8, s100
	s_mul_i32 s0, s8, 0x6280000
	s_mul_hi_i32 s1, s8, 0x6280000
	s_add_u32 s0, s34, s0
	s_addc_u32 s1, s35, s1
	v_mov_b32_e32 v36, v210
	s_cmpk_gt_i32 s12, 0x29f
	s_cbranch_scc0 .LBB0_420
	s_cmpk_gt_u32 s12, 0x2cf
	s_mov_b64 s[20:21], -1
	s_cbranch_scc0 .LBB0_428
	s_cmpk_gt_u32 s12, 0x30f
	s_cbranch_scc0 .LBB0_425
	s_cmpk_gt_u32 s12, 0x40f
	s_cbranch_scc0 .LBB0_422
	s_cmpk_gt_u32 s12, 0x98f
	s_mov_b64 s[10:11], -1
	s_cbranch_scc0 .LBB0_417
	s_add_i32 s6, s12, 0xfffff670
	s_mul_i32 s5, s8, 0x2c00000
	v_readlane_b32 s7, v254, 36
	s_mul_hi_i32 s4, s8, 0x2c00000
	s_add_u32 s18, s7, s5
	v_readlane_b32 s5, v254, 37
	s_addc_u32 s19, s5, s4
	s_add_u32 s4, s0, 0x4c80000
	s_addc_u32 s5, s1, 0
	s_mov_b64 s[10:11], 0

; __device__ __forceinline__ CvtJob cvt_decode(const Params& p, int job) {
;     CvtJob j; j.gain = nullptr;
;     const int layer = job / CT_LAYER; int r = job % CT_LAYER;
;     unsigned char* wl = p.ws + WS_W + (size_t)layer * WL_SIZE;
;     if (r < CT_IN) { j.mat = 0; j.K = 2048; j.Nsrc = INC; j.W = p.in[I_WIN] + (size_t)layer * 2048 * INC; j.gain = p.in[I_LNMIXPRE] + layer * 2048; j.dst = (bf16_t*)(wl + WL_IN); }
;     else if ((r -= CT_IN) < CT_QUP) { j.mat = 1; j.K = 512; j.Nsrc = 1536; j.W = p.in[I_WQUP] + (size_t)layer * 512 * 1536; j.gain = p.in[I_GQL] + layer * 512; j.dst = (bf16_t*)(wl + WL_QUP); }
;     else if ((r -= CT_QUP) < CT_KVUP) { j.mat = 2; j.K = 512; j.Nsrc = 2048; j.W = p.in[I_WKVUP] + (size_t)layer * 512 * 2048; j.gain = p.in[I_GKVL] + layer * 512; j.dst = (bf16_t*)(wl + WL_KVUP); }
;     else if ((r -= CT_KVUP) < CT_OUT) { j.mat = 3; j.K = 2048; j.Nsrc = 2048; j.W = p.in[I_WOUT] + (size_t)layer * 2048 * 2048; j.dst = (bf16_t*)(wl + WL_OUT); }
;     else if ((r -= CT_OUT) < CT_UP) { j.mat = 4; j.K = 2048; j.Nsrc = DFF2; j.W = p.in[I_WUP] + (size_t)layer * 2048 * DFF2; j.gain = p.in[I_LNFFNPRE] + layer * 2048; j.dst = (bf16_t*)(wl + WL_UP); }
;     else { r -= CT_UP; j.mat = 5; j.K = DFF; j.Nsrc = 2048; j.W = p.in[I_WDOWN] + (size_t)layer * DFF * 2048; j.dst = (bf16_t*)(wl + WL_DOWN); }
;     const int nKt = j.K / 128, kt = r % nKt, ntile = r / nKt; j.k0 = kt * 128; j.n0 = ntile * 128;
; template <bool PREPMAP>
; __device__ __forceinline__ void convert_jobs(const Params& p, int job0, int job_end, int stride, LAS unsigned char* lds) {
;     ...
;     for (;;) {
;         const int nj = job + stride; const bool more = nj < job_end;
;         CvtJob nxt = cur; f32x4 v2[8]; float gk2[8];
;         if (more) { nxt = cvt_decode(p, cvt_map<PREPMAP>(nj)); cvt_load(nxt, tid, v2, gk2); }
.LBB0_499:
	s_add_i32 s3, s14, 1
	s_cmp_lt_i32 s3, s29
	s_cselect_b64 s[16:17], -1, 0
	s_cmp_ge_i32 s3, s29
	s_cselect_b64 s[10:11], -1, 0
	s_and_b64 vcc, exec, s[10:11]
	s_mov_b64 s[18:19], s[4:5]
	s_mov_b32 s6, s24
	s_mov_b32 s42, s8
	s_mov_b32 s7, s28
	s_cbranch_vccnz .LBB0_584
	s_mul_hi_i32 s0, s3, 0x532ae21d
	s_lshr_b32 s1, s0, 31
	s_ashr_i32 s0, s0, 10
	s_add_i32 s36, s0, s1
	v_mul_i32_i24_e32 v0, s36, v218
	s_ashr_i32 s37, s36, 31
	v_readfirstlane_b32 s0, v0
	s_sub_i32 s7, s3, s0
	s_cmpk_gt_i32 s7, 0x98f
	s_cselect_b32 s100, 1, 0
	s_sub_i32 s36, s36, s100
	s_mul_i32 s0, s36, 0x6280000
	s_mul_hi_i32 s1, s36, 0x6280000
	s_add_u32 s0, s34, s0
	s_addc_u32 s1, s35, s1
	s_cmpk_gt_i32 s7, 0x29f
	s_cbranch_scc0 .LBB0_508
	s_cmpk_gt_u32 s7, 0x2cf
	s_mov_b64 s[44:45], -1
	s_cbranch_scc0 .LBB0_516
	s_cmpk_gt_u32 s7, 0x30f
	s_cbranch_scc0 .LBB0_513
	s_cmpk_gt_u32 s7, 0x40f
	s_cbranch_scc0 .LBB0_510
	s_cmpk_gt_u32 s7, 0x98f
	s_mov_b64 s[20:21], -1
	s_cbranch_scc0 .LBB0_506
	s_add_i32 s9, s7, 0xfffff670
	s_mul_i32 s12, s36, 0x2c00000
	v_readlane_b32 s18, v254, 36
	s_mul_hi_i32 s6, s36, 0x2c00000
	s_add_u32 s42, s18, s12
	v_readlane_b32 s12, v254, 37
	s_addc_u32 s43, s12, s6
	s_add_u32 s18, s0, 0x4c80000
	s_addc_u32 s19, s1, 0
	s_mov_b64 s[20:21], 0
